# RWKV producers: write-through (sc1) row stores, no L2 write-back at publish, flag raised after every round
# speedup vs baseline: 1.0208x; 1.0208x over previous
; DEVINL float bf2f(bf16_t v) { return __uint_as_float(((unsigned)v) << 16); }
; DEVINL float fexp2(float x) { return __builtin_amdgcn_exp2f(x); }
; DEVINL float flog2(float x) { return __builtin_amdgcn_logf(x); }
; DEVINL float sigmoidf_(float x) { return __builtin_amdgcn_rcpf(1.f + fexp2(-x * LOG2E)); }
; DEVINL void rw_project_head(const Ctx& c, int layer, int b, int hd, int pj, int nP, unsigned* cnt, unsigned char* lds) {
;     ...
;                 for (int rg = 0; rg < 4; ++rg) {
;                     const int tk = kg * 4 + rg;
;                     const bf16_t* rk = RKV + tk * 192 + nt * 16 + cl;
;                     const float rc = bf2f(rk[0]), kc = bf2f(rk[64]), vc = bf2f(rk[128]);
;                     const float u = -(w0c[nt] + aw[rg]);
;                     const float spl = fmaxf(u, 0.f) + flog2(1.f + fexp2(-fabsf(u) * LOG2E)) * (1.f / LOG2E);
;                     ldv[nt][rg] = -fexp2((-spl - 0.5f) * LOG2E) * LOG2E;
;                     const float a = sigmoidf_(a0c[nt] + aa[rg]);
;                     av[nt][rg] = a; gv[nt][rg] = ag[rg]; rcv[nt][rg] = rc;
;                     const float kr = kc * kkc[nt];
;                     kkraw[nt][rg] = kr; ss[rg] += kr * kr;
;                     kmod[nt][rg] = kc * (1.f + (a - 1.f) * kac[nt]);
.LBB0_236:
	s_mov_b32 s14, 0xbfb8aa3b
	s_waitcnt vmcnt(7)
	v_add_f32_e32 v38, v157, v38
	s_waitcnt vmcnt(2)
	v_add_f32_e32 v43, v172, v43
	v_lshlrev_b32_e32 v243, 16, v225
	v_max_f32_e64 v225, -v38, 0
	v_mul_f32_e64 v38, |v38|, s14
	v_add_f32_e32 v34, v158, v34
	v_add_f32_e32 v45, v171, v59
	v_mul_f32_e32 v43, 0xbfb8aa3b, v43
	v_exp_f32_e32 v38, v38
	v_mul_f32_e32 v34, 0xbfb8aa3b, v34
	s_waitcnt lgkmcnt(1)
	v_lshlrev_b32_e32 v44, 16, v49
	s_waitcnt lgkmcnt(0)
	v_lshlrev_b32_e32 v49, 16, v52
	v_max_f32_e64 v52, -v45, 0
	v_mul_f32_e64 v45, |v45|, s14
	v_exp_f32_e32 v43, v43
	v_exp_f32_e32 v34, v34
	v_exp_f32_e32 v45, v45
	v_add_f32_e32 v38, 1.0, v38
	v_add_f32_e32 v43, 1.0, v43
	v_log_f32_e32 v38, v38
	v_add_f32_e32 v34, 1.0, v34
	v_add_f32_e32 v45, 1.0, v45
	v_rcp_f32_e32 v43, v43
	v_rcp_f32_e32 v34, v34
	v_log_f32_e32 v45, v45
	v_fmac_f32_e32 v225, 0x3f317218, v38
	v_add_f32_e32 v59, -1.0, v43
	v_sub_f32_e32 v38, -0.5, v225
	v_add_f32_e32 v225, -1.0, v34
	v_fmac_f32_e32 v52, 0x3f317218, v45
	s_waitcnt vmcnt(0)
	v_fma_f32 v59, v174, v59, 1.0
	v_lshlrev_b32_e32 v237, 16, v226
	v_fma_f32 v225, v168, v225, 1.0
	v_add_f32_e32 v31, v153, v31
	v_sub_f32_e32 v45, -0.5, v52
	v_mul_f32_e32 v52, v173, v49
	v_mul_f32_e32 v49, v59, v49
	v_mul_f32_e32 v59, v159, v237
	v_mul_f32_e32 v225, v225, v237
	v_max_f32_e64 v237, -v31, 0
	v_mul_f32_e64 v31, |v31|, s14
	v_add_f32_e32 v27, v154, v27
	v_exp_f32_e32 v31, v31
	v_mul_f32_e32 v27, 0xbfb8aa3b, v27
	v_exp_f32_e32 v27, v27
	v_lshlrev_b32_e32 v233, 16, v223
	v_add_f32_e32 v31, 1.0, v31
	v_log_f32_e32 v31, v31
	v_add_f32_e32 v27, 1.0, v27
	v_rcp_f32_e32 v27, v27
	v_add_f32_e32 v30, v153, v30
	v_fmac_f32_e32 v237, 0x3f317218, v31
	v_sub_f32_e32 v31, -0.5, v237
	v_add_f32_e32 v237, -1.0, v27
	v_fma_f32 v237, v156, v237, 1.0
	v_mul_f32_e32 v54, v155, v233
	v_mul_f32_e32 v233, v237, v233
	v_max_f32_e64 v237, -v30, 0
	v_mul_f32_e64 v30, |v30|, s14
	v_add_f32_e32 v26, v154, v26
	v_exp_f32_e32 v30, v30
	v_mul_f32_e32 v26, 0xbfb8aa3b, v26
	v_exp_f32_e32 v26, v26
	v_lshlrev_b32_e32 v234, 16, v224
	v_add_f32_e32 v30, 1.0, v30
	v_log_f32_e32 v30, v30
	v_add_f32_e32 v26, 1.0, v26
	v_rcp_f32_e32 v26, v26
	v_add_f32_e32 v29, v153, v29
	v_fmac_f32_e32 v237, 0x3f317218, v30
	v_sub_f32_e32 v30, -0.5, v237
	v_add_f32_e32 v237, -1.0, v26
	v_fma_f32 v237, v156, v237, 1.0
	v_mul_f32_e32 v63, v155, v234
	v_mul_f32_e32 v234, v237, v234
	v_max_f32_e64 v237, -v29, 0
	v_mul_f32_e64 v29, |v29|, s14
	v_add_f32_e32 v25, v154, v25
	v_exp_f32_e32 v29, v29
	v_mul_f32_e32 v25, 0xbfb8aa3b, v25
	v_exp_f32_e32 v25, v25
	v_lshlrev_b32_e32 v235, 16, v220
	v_add_f32_e32 v29, 1.0, v29
	v_log_f32_e32 v29, v29
	v_add_f32_e32 v25, 1.0, v25
	v_rcp_f32_e32 v25, v25
	v_add_f32_e32 v28, v153, v28
	v_fmac_f32_e32 v237, 0x3f317218, v29
	v_sub_f32_e32 v29, -0.5, v237
	v_add_f32_e32 v237, -1.0, v25
	v_fma_f32 v237, v156, v237, 1.0
	v_mul_f32_e32 v72, v155, v235
	v_mul_f32_e32 v235, v237, v235
	v_max_f32_e64 v237, -v28, 0
	v_mul_f32_e64 v28, |v28|, s14
	v_add_f32_e32 v24, v154, v24
	v_exp_f32_e32 v28, v28
	v_mul_f32_e32 v24, 0xbfb8aa3b, v24
	v_exp_f32_e32 v24, v24
	v_add_f32_e32 v41, v172, v41
	v_add_f32_e32 v57, v171, v57
	v_mul_f32_e32 v41, 0xbfb8aa3b, v41
	v_add_f32_e32 v28, 1.0, v28
	v_max_f32_e64 v68, -v57, 0
	v_mul_f32_e64 v57, |v57|, s14
	v_exp_f32_e32 v41, v41
	v_log_f32_e32 v28, v28
	v_add_f32_e32 v24, 1.0, v24
	v_exp_f32_e32 v57, v57
	v_rcp_f32_e32 v24, v24
	v_add_f32_e32 v41, 1.0, v41
	v_fmac_f32_e32 v237, 0x3f317218, v28
	v_add_f32_e32 v57, 1.0, v57
	v_rcp_f32_e32 v41, v41
	v_add_f32_e32 v39, v157, v39
	v_sub_f32_e32 v28, -0.5, v237
	v_add_f32_e32 v237, -1.0, v24
	v_lshlrev_b32_e32 v223, 16, v219
	v_log_f32_e32 v57, v57
	v_lshlrev_b32_e32 v236, 16, v217
	v_max_f32_e64 v219, -v39, 0
	v_mul_f32_e64 v39, |v39|, s14
	v_add_f32_e32 v35, v158, v35
	v_fma_f32 v237, v156, v237, 1.0
	v_add_f32_e32 v15, v79, v15
	v_mul_f32_e32 v217, v155, v236
	v_exp_f32_e32 v39, v39
	v_mul_f32_e32 v35, 0xbfb8aa3b, v35
	v_mul_f32_e32 v236, v237, v236
	v_max_f32_e64 v237, -v15, 0
	v_mul_f32_e64 v15, |v15|, s14
	v_exp_f32_e32 v35, v35
	v_exp_f32_e32 v15, v15
	v_add_f32_e32 v150, -1.0, v41
	v_add_f32_e32 v40, v172, v40
	v_lshlrev_b32_e32 v67, 16, v67
	v_fmac_f32_e32 v68, 0x3f317218, v57
	v_fma_f32 v150, v174, v150, 1.0
	v_add_f32_e32 v56, v171, v56
	v_mul_f32_e32 v40, 0xbfb8aa3b, v40
	v_sub_f32_e32 v57, -0.5, v68
	v_mul_f32_e32 v68, v173, v67
	v_mul_f32_e32 v67, v150, v67
	v_max_f32_e64 v150, -v56, 0
	v_mul_f32_e64 v56, |v56|, s14
	v_exp_f32_e32 v40, v40
	v_add_f32_e32 v39, 1.0, v39
	v_add_f32_e32 v11, v87, v11
	v_exp_f32_e32 v56, v56
	v_log_f32_e32 v39, v39
	v_add_f32_e32 v35, 1.0, v35
	v_add_f32_e32 v15, 1.0, v15
	v_mul_f32_e32 v11, 0xbfb8aa3b, v11
	v_rcp_f32_e32 v35, v35
	v_log_f32_e32 v15, v15
	v_exp_f32_e32 v11, v11
	v_add_f32_e32 v40, 1.0, v40
	v_add_f32_e32 v56, 1.0, v56
	v_rcp_f32_e32 v40, v40
	v_fmac_f32_e32 v219, 0x3f317218, v39
	v_log_f32_e32 v56, v56
	v_sub_f32_e32 v39, -0.5, v219
	v_add_f32_e32 v219, -1.0, v35
	v_fmac_f32_e32 v237, 0x3f317218, v15
	v_add_f32_e32 v11, 1.0, v11
	v_lshlrev_b32_e32 v232, 16, v228
	v_fma_f32 v219, v168, v219, 1.0
	v_add_f32_e32 v36, v157, v36
	v_sub_f32_e32 v15, -0.5, v237
	v_rcp_f32_e32 v237, v11
	v_mul_f32_e32 v47, v159, v232
	v_mul_f32_e32 v219, v219, v232
	v_max_f32_e64 v232, -v36, 0
	v_mul_f32_e64 v36, |v36|, s14
	v_add_f32_e32 v32, v158, v32
	v_lshlrev_b32_e32 v242, 16, v227
	v_lshlrev_b32_e32 v227, 16, v215
	v_add_f32_e32 v215, -1.0, v40
	v_exp_f32_e32 v36, v36
	v_mul_f32_e32 v32, 0xbfb8aa3b, v32
	v_lshlrev_b32_e32 v66, 16, v55
	v_add_f32_e32 v55, v171, v58
	v_lshlrev_b32_e32 v73, 16, v73
	v_fmac_f32_e32 v150, 0x3f317218, v56
;     DEVINL bf16_t* VF() const { return (bf16_t*)(ws + OFF_VF); }
; DEVINL bf16_t f2bf(float f) { return (bf16_t)(cvt_pk_bf16(f, 0.f) & 0xffffu); }
; DEVINL float bf2f(bf16_t v) { return __uint_as_float(((unsigned)v) << 16); }
; DEVINL float fexp2(float x) { return __builtin_amdgcn_exp2f(x); }
; DEVINL float flog2(float x) { return __builtin_amdgcn_logf(x); }
; DEVINL float sigmoidf_(float x) { return __builtin_amdgcn_rcpf(1.f + fexp2(-x * LOG2E)); }
; DEVINL float row16_sum(float v) { v += DPPF(v, 0xB1); v += DPPF(v, 0x4E); v += DPPF(v, 0x141); v += DPPF(v, 0x140); return v; }
; DEVINL void rw_project_head(const Ctx& c, int layer, int b, int hd, int pj, int nP, unsigned* cnt, unsigned char* lds) {
;     ...
;                     const float rc = bf2f(rk[0]), kc = bf2f(rk[64]), vc = bf2f(rk[128]);
;                     const float u = -(w0c[nt] + aw[rg]);
;                     const float spl = fmaxf(u, 0.f) + flog2(1.f + fexp2(-fabsf(u) * LOG2E)) * (1.f / LOG2E);
;                     ldv[nt][rg] = -fexp2((-spl - 0.5f) * LOG2E) * LOG2E;
;                     const float a = sigmoidf_(a0c[nt] + aa[rg]);
;                     av[nt][rg] = a; gv[nt][rg] = ag[rg]; rcv[nt][rg] = rc;
;                     const float kr = kc * kkc[nt];
;                     kkraw[nt][rg] = kr; ss[rg] += kr * kr;
;                     kmod[nt][rg] = kc * (1.f + (a - 1.f) * kac[nt]);
;                     const size_t o = (size_t)(t0 + tk) * 512 + hd * 64 + nt * 16 + cl;
;                     float vo = vc;
;                     if (layer == 0) c.VF()[o] = f2bf(vc);
;                     else { const float vf = bf2f(c.VF()[o]); vo = vc + (vf - vc) * sigmoidf_(v0c[nt] + avv[rg]); }
;                     vout[nt][rg] = vo;
;                 }
;             }
;             float inv[4];
; #pragma unroll
;             for (int rg = 0; rg < 4; ++rg) inv[rg] = fminf(__builtin_amdgcn_rsqf(row16_sum(ss[rg])), 1e12f);
	v_fma_f32 v215, v174, v215, 1.0
	v_add_f32_e32 v37, v157, v37
	v_exp_f32_e32 v32, v32
	v_max_f32_e64 v58, -v55, 0
	v_mul_f32_e64 v55, |v55|, s14
	v_add_f32_e32 v42, v172, v42
	v_sub_f32_e32 v56, -0.5, v150
	v_mul_f32_e32 v150, v173, v73
	v_mul_f32_e32 v73, v215, v73
	v_lshlrev_b32_e32 v215, 16, v231
	v_max_f32_e64 v231, -v37, 0
	v_mul_f32_e64 v37, |v37|, s14
	v_add_f32_e32 v33, v158, v33
	v_add_f32_e32 v11, -1.0, v237
	v_lshlrev_b32_e32 v222, 16, v222
	v_exp_f32_e32 v55, v55
	v_mul_f32_e32 v42, 0xbfb8aa3b, v42
	v_exp_f32_e32 v37, v37
	v_mul_f32_e32 v33, 0xbfb8aa3b, v33
	v_fma_f32 v11, v115, v11, 1.0
	v_mul_f32_e32 v61, v113, v222
	v_exp_f32_e32 v42, v42
	v_exp_f32_e32 v33, v33
	v_add_f32_e32 v36, 1.0, v36
	v_mul_f32_e32 v222, v11, v222
	v_add_f32_e32 v11, v79, v14
	v_log_f32_e32 v36, v36
	v_add_f32_e32 v32, 1.0, v32
	v_max_f32_e64 v14, -v11, 0
	v_mul_f32_e64 v11, |v11|, s14
	v_add_f32_e32 v9, v87, v9
	v_rcp_f32_e32 v32, v32
	v_exp_f32_e32 v11, v11
	v_mul_f32_e32 v9, 0xbfb8aa3b, v9
	v_add_f32_e32 v55, 1.0, v55
	v_add_f32_e32 v37, 1.0, v37
	v_exp_f32_e32 v9, v9
	v_log_f32_e32 v55, v55
	v_add_f32_e32 v42, 1.0, v42
	v_log_f32_e32 v37, v37
	v_add_f32_e32 v33, 1.0, v33
	v_add_f32_e32 v10, v87, v10
	v_rcp_f32_e32 v42, v42
	v_rcp_f32_e32 v33, v33
	v_fmac_f32_e32 v232, 0x3f317218, v36
	v_mul_f32_e32 v10, 0xbfb8aa3b, v10
	v_sub_f32_e32 v36, -0.5, v232
	v_add_f32_e32 v232, -1.0, v32
	v_add_f32_e32 v11, 1.0, v11
	v_exp_f32_e32 v10, v10
	v_fma_f32 v232, v168, v232, 1.0
	v_log_f32_e32 v11, v11
	v_add_f32_e32 v9, 1.0, v9
	v_add_f32_e32 v8, v87, v8
	v_fmac_f32_e32 v58, 0x3f317218, v55
	v_mul_f32_e32 v151, v159, v243
	v_fmac_f32_e32 v231, 0x3f317218, v37
	v_mul_f32_e32 v232, v232, v243
	v_rcp_f32_e32 v243, v9
	v_mul_f32_e32 v8, 0xbfb8aa3b, v8
	v_sub_f32_e32 v55, -0.5, v58
	v_add_f32_e32 v58, -1.0, v42
	v_sub_f32_e32 v37, -0.5, v231
	v_add_f32_e32 v231, -1.0, v33
	v_exp_f32_e32 v8, v8
	v_fma_f32 v58, v174, v58, 1.0
	v_fma_f32 v231, v168, v231, 1.0
	v_add_f32_e32 v10, 1.0, v10
	v_mul_f32_e32 v60, v173, v66
	v_mul_f32_e32 v58, v58, v66
	v_mul_f32_e32 v66, v159, v242
	v_mul_f32_e32 v231, v231, v242
	v_fmac_f32_e32 v14, 0x3f317218, v11
	v_rcp_f32_e32 v242, v10
	v_sub_f32_e32 v11, -0.5, v14
	v_add_f32_e32 v9, -1.0, v243
	v_lshlrev_b32_e32 v226, 16, v216
	v_mul_f32_e32 v11, 0x3fb8aa3b, v11
	v_fma_f32 v9, v115, v9, 1.0
	v_add_f32_e32 v8, 1.0, v8
	v_mul_f32_e32 v216, v113, v226
	v_exp_f32_e32 v11, v11
	v_mul_f32_e32 v226, v9, v226
	v_lshlrev_b32_e32 v9, 16, v201
	v_rcp_f32_e32 v201, v8
	v_add_f32_e32 v10, -1.0, v242
	v_mul_f32_e32 v224, v113, v227
	v_mul_f32_e32 v228, v217, v217
	v_fma_f32 v10, v115, v10, 1.0
	v_mul_f32_e32 v71, v113, v223
	v_fmac_f32_e32 v228, v224, v224
	v_mul_f32_e32 v223, v10, v223
	v_add_f32_e32 v10, v79, v13
	v_fmac_f32_e32 v228, v151, v151
	v_mul_f32_e32 v14, 0xbfb8aa3b, v11
	v_max_f32_e64 v11, -v10, 0
	v_mul_f32_e64 v10, |v10|, s14
	v_add_f32_e32 v8, -1.0, v201
	v_fmac_f32_e32 v228, v150, v150
	v_exp_f32_e32 v10, v10
	v_fma_f32 v8, v115, v8, 1.0
	v_mul_f32_e32 v227, v8, v227
	v_mul_f32_e32 v220, v72, v72
	v_add_f32_dpp v8, v228, v228 quad_perm:[1,0,3,2] row_mask:0xf bank_mask:0xf bound_ctrl:1
	v_add_f32_e32 v10, 1.0, v10
	v_log_f32_e32 v10, v10
	v_add_f32_dpp v8, v8, v8 quad_perm:[2,3,0,1] row_mask:0xf bank_mask:0xf bound_ctrl:1
	v_fmac_f32_e32 v220, v216, v216
	v_fmac_f32_e32 v220, v66, v66
	v_add_f32_dpp v8, v8, v8 row_half_mirror row_mask:0xf bank_mask:0xf bound_ctrl:1
	v_fmac_f32_e32 v220, v68, v68
	v_fmac_f32_e32 v11, 0x3f317218, v10
	v_add_f32_dpp v8, v8, v8 row_mirror row_mask:0xf bank_mask:0xf bound_ctrl:1
	v_rsq_f32_e32 v8, v8
	v_sub_f32_e32 v10, -0.5, v11
	v_mul_f32_e32 v10, 0x3fb8aa3b, v10
	v_exp_f32_e32 v10, v10
	v_min_f32_e32 v228, 0x5368d4a5, v8
	v_add_f32_dpp v8, v220, v220 quad_perm:[1,0,3,2] row_mask:0xf bank_mask:0xf bound_ctrl:1
	v_mul_f32_e32 v77, v63, v63
	v_fmac_f32_e32 v77, v71, v71
	v_add_f32_dpp v8, v8, v8 quad_perm:[2,3,0,1] row_mask:0xf bank_mask:0xf bound_ctrl:1
	v_fmac_f32_e32 v77, v59, v59
	v_fmac_f32_e32 v77, v60, v60
	v_add_f32_dpp v8, v8, v8 row_half_mirror row_mask:0xf bank_mask:0xf bound_ctrl:1
	v_mul_f32_e32 v13, 0xbfb8aa3b, v10
	v_add_f32_e32 v10, v79, v12
	v_add_f32_dpp v8, v8, v8 row_mirror row_mask:0xf bank_mask:0xf bound_ctrl:1
	v_rsq_f32_e32 v8, v8
	v_max_f32_e64 v11, -v10, 0
	v_mul_f32_e64 v10, |v10|, s14
	v_exp_f32_e32 v10, v10
	v_min_f32_e32 v220, 0x5368d4a5, v8
	v_add_f32_dpp v8, v77, v77 quad_perm:[1,0,3,2] row_mask:0xf bank_mask:0xf bound_ctrl:1
	v_mul_f32_e32 v69, v54, v54
	v_fmac_f32_e32 v69, v61, v61
	v_add_f32_dpp v8, v8, v8 quad_perm:[2,3,0,1] row_mask:0xf bank_mask:0xf bound_ctrl:1
	v_add_f32_e32 v10, 1.0, v10
	v_fmac_f32_e32 v69, v47, v47
	v_add_f32_dpp v8, v8, v8 row_half_mirror row_mask:0xf bank_mask:0xf bound_ctrl:1
	v_log_f32_e32 v10, v10
	v_fmac_f32_e32 v69, v52, v52
	v_add_f32_dpp v8, v8, v8 row_mirror row_mask:0xf bank_mask:0xf bound_ctrl:1
	v_rsq_f32_e32 v8, v8
	v_fmac_f32_e32 v11, 0x3f317218, v10
	v_sub_f32_e32 v10, -0.5, v11
	v_mul_f32_e32 v10, 0x3fb8aa3b, v10
	v_min_f32_e32 v77, 0x5368d4a5, v8
	v_add_f32_dpp v8, v69, v69 quad_perm:[1,0,3,2] row_mask:0xf bank_mask:0xf bound_ctrl:1
	v_exp_f32_e32 v10, v10
	v_readlane_b32 s22, v245, 28
	v_add_f32_dpp v8, v8, v8 quad_perm:[2,3,0,1] row_mask:0xf bank_mask:0xf bound_ctrl:1
	v_cvt_pk_bf16_f32 v244, v9, s0
	v_readlane_b32 s23, v245, 29
	v_add_f32_dpp v8, v8, v8 row_half_mirror row_mask:0xf bank_mask:0xf bound_ctrl:1
	v_readlane_b32 s14, v247, 30
	v_mul_f32_e32 v12, 0xbfb8aa3b, v10
	v_add_f32_dpp v8, v8, v8 row_mirror row_mask:0xf bank_mask:0xf bound_ctrl:1
	v_rsq_f32_e32 v8, v8
	v_readlane_b32 s15, v247, 31
	v_cvt_pk_bf16_f32 v12, v12, s0
; DEVINL bf16_t f2bf(float f) { return (bf16_t)(cvt_pk_bf16(f, 0.f) & 0xffffu); }
; DEVINL void rw_project_head(const Ctx& c, int layer, int b, int hd, int pj, int nP, unsigned* cnt, unsigned char* lds) {
;     ...
;             for (int nt = 0; nt < 4; ++nt)
; #pragma unroll
;                 for (int rg = 0; rg < 4; ++rg) {
;                     const size_t o = (size_t)(t0 + kg * 4 + rg) * 512 + hd * 64 + nt * 16 + cl;
;                     const float kk = kkraw[nt][rg] * inv[rg];
;                     R[o] = f2bf(rcv[nt][rg]); LD[o] = f2bf(ldv[nt][rg]); KP[o] = f2bf(kmod[nt][rg]); VP[o] = f2bf(vout[nt][rg]);
;                     KK[o] = f2bf(kk); BB[o] = f2bf(kk * av[nt][rg]); GG[o] = f2bf(gv[nt][rg]);
	v_readlane_b32 s24, v247, 32
	v_min_f32_e32 v69, 0x5368d4a5, v8
	v_lshrrev_b32_e32 v251, 6, v160
	v_mul_u32_u24_e32 v251, 0x3d00, v251
	v_add_u32_e32 v251, 0x9400, v251
	v_lshlrev_b64 v[8:9], 1, v[128:129]
	v_lshrrev_b32_e32 v248, 3, v8
	v_and_b32_e32 v248, 0x780, v248
	v_and_b32_e32 v250, 0x7e, v8
	v_add3_u32 v248, v248, v250, v251
	v_mov_b32_e32 v10, v248
	ds_write_b16 v10, v244
	v_add_u32_e32 v10, 0x800, v248
	ds_write_b16 v10, v12
	v_cvt_pk_bf16_f32 v12, v227, s0
	v_add_u32_e32 v10, 0x1000, v248
	v_readlane_b32 s25, v247, 33
	v_readlane_b32 s28, v247, 34
	v_mul_f32_e32 v224, v224, v228
	ds_write_b16 v10, v12
	v_cvt_pk_bf16_f32 v12, v64, s0
	v_add_u32_e32 v10, 0x1800, v248
	v_readlane_b32 s29, v247, 35
	ds_write_b16 v10, v12
	v_cvt_pk_bf16_f32 v12, v224, s0
	v_add_u32_e32 v10, 0x2000, v248
	v_readlane_b32 s30, v247, 36
	v_readlane_b32 s34, v247, 38
	ds_write_b16 v10, v12
	v_mul_f32_e32 v10, v201, v224
	v_readlane_b32 s31, v247, 37
	v_readlane_b32 s35, v247, 39
	v_cvt_pk_bf16_f32 v12, v10, s0
	v_add_u32_e32 v10, 0x2800, v248
	v_cvt_pk_bf16_f32 v0, v0, s0
	v_add_u32_e32 v8, 0x3000, v248
	v_lshlrev_b32_e32 v206, 16, v206
	ds_write_b16 v8, v0
	v_lshlrev_b64 v[8:9], 1, v[130:131]
	v_lshrrev_b32_e32 v248, 3, v8
	v_and_b32_e32 v248, 0x780, v248
	v_and_b32_e32 v250, 0x7e, v8
	v_add3_u32 v248, v248, v250, v251
	ds_write_b16 v10, v12
	v_cvt_pk_bf16_f32 v12, v206, s0
	v_mov_b32_e32 v10, v248
	ds_write_b16 v10, v12
	v_cvt_pk_bf16_f32 v12, v13, s0
	v_add_u32_e32 v10, 0x800, v248
	ds_write_b16 v10, v12
	v_cvt_pk_bf16_f32 v12, v226, s0
	v_add_u32_e32 v10, 0x1000, v248
	v_mul_f32_e32 v0, v216, v220
	ds_write_b16 v10, v12
	v_cvt_pk_bf16_f32 v12, v119, s0
	v_add_u32_e32 v10, 0x1800, v248
	ds_write_b16 v10, v12
	v_cvt_pk_bf16_f32 v12, v0, s0
	v_add_u32_e32 v10, 0x2000, v248
	v_mul_f32_e32 v0, v243, v0
	ds_write_b16 v10, v12
	v_cvt_pk_bf16_f32 v0, v0, s0
	v_add_u32_e32 v10, 0x2800, v248
	ds_write_b16 v10, v0
	v_cvt_pk_bf16_f32 v10, v1, s0
	v_add_u32_e32 v0, 0x3000, v248
	v_lshlrev_b32_e32 v210, 16, v210
	ds_write_b16 v0, v10
	v_lshlrev_b64 v[0:1], 1, v[132:133]
	v_lshrrev_b32_e32 v249, 3, v0
	v_and_b32_e32 v249, 0x780, v249
	v_and_b32_e32 v250, 0x7e, v0
	v_add3_u32 v249, v249, v250, v251
	v_cvt_pk_bf16_f32 v11, v210, s0
	v_mov_b32_e32 v8, v249
	ds_write_b16 v8, v11
	v_cvt_pk_bf16_f32 v11, v14, s0
	v_add_u32_e32 v8, 0x800, v249
	ds_write_b16 v8, v11
	v_cvt_pk_bf16_f32 v11, v223, s0
	v_add_u32_e32 v8, 0x1000, v249
	v_mul_f32_e32 v15, 0x3fb8aa3b, v15
	v_mul_f32_e32 v10, v71, v77
	ds_write_b16 v8, v11
	v_cvt_pk_bf16_f32 v11, v199, s0
	v_add_u32_e32 v8, 0x1800, v249
	v_exp_f32_e32 v15, v15
	ds_write_b16 v8, v11
	v_cvt_pk_bf16_f32 v11, v10, s0
	v_add_u32_e32 v8, 0x2000, v249
	ds_write_b16 v8, v11
	v_mul_f32_e32 v8, v242, v10
	v_cvt_pk_bf16_f32 v10, v8, s0
	v_add_u32_e32 v8, 0x2800, v249
	v_cvt_pk_bf16_f32 v2, v2, s0
	v_add_u32_e32 v0, 0x3000, v249
	v_lshlrev_b32_e32 v211, 16, v211
	ds_write_b16 v0, v2
	v_lshlrev_b64 v[0:1], 1, v[134:135]
	v_lshrrev_b32_e32 v249, 3, v0
	v_and_b32_e32 v249, 0x780, v249
	v_and_b32_e32 v250, 0x7e, v0
	v_add3_u32 v249, v249, v250, v251
	v_mul_f32_e32 v15, 0xbfb8aa3b, v15
	ds_write_b16 v8, v10
	v_cvt_pk_bf16_f32 v10, v211, s0
	v_mov_b32_e32 v8, v249
	ds_write_b16 v8, v10
	v_cvt_pk_bf16_f32 v10, v15, s0
	v_add_u32_e32 v8, 0x800, v249
	ds_write_b16 v8, v10
	v_cvt_pk_bf16_f32 v10, v222, s0
	v_add_u32_e32 v8, 0x1000, v249
	v_mul_f32_e32 v28, 0x3fb8aa3b, v28
	v_mul_f32_e32 v2, v61, v69
	ds_write_b16 v8, v10
	v_cvt_pk_bf16_f32 v10, v200, s0
	v_add_u32_e32 v8, 0x1800, v249
	v_exp_f32_e32 v28, v28
	ds_write_b16 v8, v10
	v_cvt_pk_bf16_f32 v10, v2, s0
	v_add_u32_e32 v8, 0x2000, v249
	v_mul_f32_e32 v2, v237, v2
	ds_write_b16 v8, v10
	v_cvt_pk_bf16_f32 v2, v2, s0
	v_add_u32_e32 v8, 0x2800, v249
	ds_write_b16 v8, v2
	v_cvt_pk_bf16_f32 v2, v3, s0
	v_add_u32_e32 v0, 0x3000, v249
	v_lshlrev_b32_e32 v212, 16, v212
	ds_write_b16 v0, v2
	v_lshlrev_b64 v[0:1], 1, v[136:137]
	v_lshrrev_b32_e32 v249, 3, v0
	v_and_b32_e32 v249, 0x780, v249
	v_and_b32_e32 v250, 0x7e, v0
	v_add3_u32 v249, v249, v250, v251
	v_mul_f32_e32 v28, 0xbfb8aa3b, v28
	v_cvt_pk_bf16_f32 v9, v212, s0
	v_mov_b32_e32 v2, v249
	ds_write_b16 v2, v9
	v_cvt_pk_bf16_f32 v9, v28, s0
	v_add_u32_e32 v2, 0x800, v249
	ds_write_b16 v2, v9
	v_cvt_pk_bf16_f32 v9, v236, s0
	v_add_u32_e32 v2, 0x1000, v249
	v_mul_f32_e32 v8, v217, v228
	ds_write_b16 v2, v9
	v_cvt_pk_bf16_f32 v9, v202, s0
	v_add_u32_e32 v2, 0x1800, v249
	v_mul_f32_e32 v29, 0x3fb8aa3b, v29
	ds_write_b16 v2, v9
	v_cvt_pk_bf16_f32 v9, v8, s0
	v_add_u32_e32 v2, 0x2000, v249
	v_exp_f32_e32 v29, v29
	ds_write_b16 v2, v9
	v_mul_f32_e32 v2, v24, v8
	v_cvt_pk_bf16_f32 v8, v2, s0
	v_add_u32_e32 v2, 0x2800, v249
	ds_write_b16 v2, v8
	v_cvt_pk_bf16_f32 v2, v4, s0
	v_add_u32_e32 v0, 0x3000, v249
	v_lshlrev_b32_e32 v213, 16, v213
	ds_write_b16 v0, v2
	v_lshlrev_b64 v[0:1], 1, v[138:139]
	v_lshrrev_b32_e32 v249, 3, v0
	v_and_b32_e32 v249, 0x780, v249
	v_and_b32_e32 v250, 0x7e, v0
	v_add3_u32 v249, v249, v250, v251
	v_mul_f32_e32 v29, 0xbfb8aa3b, v29
	v_cvt_pk_bf16_f32 v8, v213, s0
	v_mov_b32_e32 v2, v249
	ds_write_b16 v2, v8
	v_cvt_pk_bf16_f32 v8, v29, s0
	v_add_u32_e32 v2, 0x800, v249
	ds_write_b16 v2, v8
	v_cvt_pk_bf16_f32 v8, v235, s0
	v_add_u32_e32 v2, 0x1000, v249
	v_mul_f32_e32 v4, v72, v220
	ds_write_b16 v2, v8
	v_cvt_pk_bf16_f32 v8, v203, s0
	v_add_u32_e32 v2, 0x1800, v249
	v_mul_f32_e32 v30, 0x3fb8aa3b, v30
	ds_write_b16 v2, v8
	v_cvt_pk_bf16_f32 v8, v4, s0
	v_add_u32_e32 v2, 0x2000, v249
	v_exp_f32_e32 v30, v30
	ds_write_b16 v2, v8
	v_mul_f32_e32 v2, v25, v4
	v_cvt_pk_bf16_f32 v4, v2, s0
	v_add_u32_e32 v2, 0x2800, v249
	ds_write_b16 v2, v4
; DEVINL bf16_t f2bf(float f) { return (bf16_t)(cvt_pk_bf16(f, 0.f) & 0xffffu); }
; DEVINL void rw_project_head(const Ctx& c, int layer, int b, int hd, int pj, int nP, unsigned* cnt, unsigned char* lds) {
;     ...
;             for (int nt = 0; nt < 4; ++nt)
; #pragma unroll
;                 for (int rg = 0; rg < 4; ++rg) {
;                     const size_t o = (size_t)(t0 + kg * 4 + rg) * 512 + hd * 64 + nt * 16 + cl;
;                     const float kk = kkraw[nt][rg] * inv[rg];
;                     R[o] = f2bf(rcv[nt][rg]); LD[o] = f2bf(ldv[nt][rg]); KP[o] = f2bf(kmod[nt][rg]); VP[o] = f2bf(vout[nt][rg]);
;                     KK[o] = f2bf(kk); BB[o] = f2bf(kk * av[nt][rg]); GG[o] = f2bf(gv[nt][rg]);
	v_cvt_pk_bf16_f32 v2, v5, s0
	v_add_u32_e32 v0, 0x3000, v249
	v_lshlrev_b32_e32 v214, 16, v214
	ds_write_b16 v0, v2
	v_lshlrev_b64 v[0:1], 1, v[140:141]
	v_lshrrev_b32_e32 v249, 3, v0
	v_and_b32_e32 v249, 0x780, v249
	v_and_b32_e32 v250, 0x7e, v0
	v_add3_u32 v249, v249, v250, v251
	v_mul_f32_e32 v30, 0xbfb8aa3b, v30
	v_cvt_pk_bf16_f32 v5, v214, s0
	v_mov_b32_e32 v2, v249
	ds_write_b16 v2, v5
	v_cvt_pk_bf16_f32 v5, v30, s0
	v_add_u32_e32 v2, 0x800, v249
	ds_write_b16 v2, v5
	v_cvt_pk_bf16_f32 v5, v234, s0
	v_add_u32_e32 v2, 0x1000, v249
	v_mul_f32_e32 v4, v63, v77
	ds_write_b16 v2, v5
	v_cvt_pk_bf16_f32 v5, v204, s0
	v_add_u32_e32 v2, 0x1800, v249
	v_mul_f32_e32 v31, 0x3fb8aa3b, v31
	ds_write_b16 v2, v5
	v_cvt_pk_bf16_f32 v5, v4, s0
	v_add_u32_e32 v2, 0x2000, v249
	v_exp_f32_e32 v31, v31
	ds_write_b16 v2, v5
	v_mul_f32_e32 v2, v26, v4
	v_cvt_pk_bf16_f32 v4, v2, s0
	v_add_u32_e32 v2, 0x2800, v249
	ds_write_b16 v2, v4
	v_cvt_pk_bf16_f32 v2, v6, s0
	v_add_u32_e32 v0, 0x3000, v249
	v_lshlrev_b32_e32 v218, 16, v218
	ds_write_b16 v0, v2
	v_lshlrev_b64 v[0:1], 1, v[142:143]
	v_lshrrev_b32_e32 v249, 3, v0
	v_and_b32_e32 v249, 0x780, v249
	v_and_b32_e32 v250, 0x7e, v0
	v_add3_u32 v249, v249, v250, v251
	v_mul_f32_e32 v31, 0xbfb8aa3b, v31
	v_cvt_pk_bf16_f32 v5, v218, s0
	v_mov_b32_e32 v2, v249
	ds_write_b16 v2, v5
	v_cvt_pk_bf16_f32 v5, v31, s0
	v_add_u32_e32 v2, 0x800, v249
	ds_write_b16 v2, v5
	v_cvt_pk_bf16_f32 v5, v233, s0
	v_add_u32_e32 v2, 0x1000, v249
	v_mul_f32_e32 v4, v54, v69
	ds_write_b16 v2, v5
	v_cvt_pk_bf16_f32 v5, v205, s0
	v_add_u32_e32 v2, 0x1800, v249
	v_mul_f32_e32 v36, 0x3fb8aa3b, v36
	ds_write_b16 v2, v5
	v_cvt_pk_bf16_f32 v5, v4, s0
	v_add_u32_e32 v2, 0x2000, v249
	v_exp_f32_e32 v36, v36
	ds_write_b16 v2, v5
	v_mul_f32_e32 v2, v27, v4
	v_cvt_pk_bf16_f32 v4, v2, s0
	v_add_u32_e32 v2, 0x2800, v249
	ds_write_b16 v2, v4
	v_cvt_pk_bf16_f32 v2, v7, s0
	v_add_u32_e32 v0, 0x3000, v249
	v_lshlrev_b32_e32 v230, 16, v230
	ds_write_b16 v0, v2
	v_lshlrev_b64 v[0:1], 1, v[144:145]
	v_lshrrev_b32_e32 v249, 3, v0
	v_and_b32_e32 v249, 0x780, v249
	v_and_b32_e32 v250, 0x7e, v0
	v_add3_u32 v249, v249, v250, v251
	v_mul_f32_e32 v36, 0xbfb8aa3b, v36
	v_cvt_pk_bf16_f32 v5, v230, s0
	v_mov_b32_e32 v2, v249
	ds_write_b16 v2, v5
	v_cvt_pk_bf16_f32 v5, v36, s0
	v_add_u32_e32 v2, 0x800, v249
	ds_write_b16 v2, v5
	v_cvt_pk_bf16_f32 v5, v232, s0
	v_add_u32_e32 v2, 0x1000, v249
	v_mul_f32_e32 v4, v151, v228
	ds_write_b16 v2, v5
	v_cvt_pk_bf16_f32 v5, v207, s0
	v_add_u32_e32 v2, 0x1800, v249
	v_mul_f32_e32 v37, 0x3fb8aa3b, v37
	ds_write_b16 v2, v5
	v_cvt_pk_bf16_f32 v5, v4, s0
	v_add_u32_e32 v2, 0x2000, v249
	v_exp_f32_e32 v37, v37
	ds_write_b16 v2, v5
	v_mul_f32_e32 v2, v32, v4
	v_cvt_pk_bf16_f32 v4, v2, s0
	v_add_u32_e32 v2, 0x2800, v249
	ds_write_b16 v2, v4
	v_cvt_pk_bf16_f32 v2, v16, s0
	v_add_u32_e32 v0, 0x3000, v249
	v_lshlrev_b32_e32 v229, 16, v229
	ds_write_b16 v0, v2
	v_lshlrev_b64 v[0:1], 1, v[146:147]
	v_lshrrev_b32_e32 v249, 3, v0
	v_and_b32_e32 v249, 0x780, v249
	v_and_b32_e32 v250, 0x7e, v0
	v_add3_u32 v249, v249, v250, v251
	v_mul_f32_e32 v37, 0xbfb8aa3b, v37
	v_cvt_pk_bf16_f32 v5, v229, s0
	v_mov_b32_e32 v2, v249
	ds_write_b16 v2, v5
	v_cvt_pk_bf16_f32 v5, v37, s0
	v_add_u32_e32 v2, 0x800, v249
	ds_write_b16 v2, v5
	v_cvt_pk_bf16_f32 v5, v231, s0
	v_add_u32_e32 v2, 0x1000, v249
	v_mul_f32_e32 v4, v66, v220
	ds_write_b16 v2, v5
	v_cvt_pk_bf16_f32 v5, v208, s0
	v_add_u32_e32 v2, 0x1800, v249
	v_mul_f32_e32 v38, 0x3fb8aa3b, v38
	ds_write_b16 v2, v5
	v_cvt_pk_bf16_f32 v5, v4, s0
	v_add_u32_e32 v2, 0x2000, v249
	v_exp_f32_e32 v38, v38
	ds_write_b16 v2, v5
	v_mul_f32_e32 v2, v33, v4
	v_cvt_pk_bf16_f32 v4, v2, s0
	v_add_u32_e32 v2, 0x2800, v249
	ds_write_b16 v2, v4
	v_cvt_pk_bf16_f32 v2, v17, s0
	v_add_u32_e32 v0, 0x3000, v249
	v_lshlrev_b32_e32 v221, 16, v221
	ds_write_b16 v0, v2
	v_lshlrev_b64 v[0:1], 1, v[74:75]
	v_lshrrev_b32_e32 v249, 3, v0
	v_and_b32_e32 v249, 0x780, v249
	v_and_b32_e32 v250, 0x7e, v0
	v_add3_u32 v249, v249, v250, v251
	v_mul_f32_e32 v38, 0xbfb8aa3b, v38
	v_cvt_pk_bf16_f32 v5, v221, s0
	v_mov_b32_e32 v2, v249
	ds_write_b16 v2, v5
	v_cvt_pk_bf16_f32 v5, v38, s0
	v_add_u32_e32 v2, 0x800, v249
	ds_write_b16 v2, v5
	v_cvt_pk_bf16_f32 v5, v225, s0
	v_add_u32_e32 v2, 0x1000, v249
	v_mul_f32_e32 v4, v59, v77
	ds_write_b16 v2, v5
	v_cvt_pk_bf16_f32 v5, v209, s0
	v_add_u32_e32 v2, 0x1800, v249
	v_mul_f32_e32 v39, 0x3fb8aa3b, v39
	ds_write_b16 v2, v5
	v_cvt_pk_bf16_f32 v5, v4, s0
	v_add_u32_e32 v2, 0x2000, v249
	v_exp_f32_e32 v39, v39
	ds_write_b16 v2, v5
	v_mul_f32_e32 v2, v34, v4
	v_cvt_pk_bf16_f32 v4, v2, s0
	v_add_u32_e32 v2, 0x2800, v249
	ds_write_b16 v2, v4
	v_cvt_pk_bf16_f32 v2, v18, s0
	v_add_u32_e32 v0, 0x3000, v249
	ds_write_b16 v0, v2
	v_lshlrev_b64 v[0:1], 1, v[148:149]
	v_lshrrev_b32_e32 v249, 3, v0
	v_and_b32_e32 v249, 0x780, v249
	v_and_b32_e32 v250, 0x7e, v0
	v_add3_u32 v249, v249, v250, v251
	v_mul_f32_e32 v39, 0xbfb8aa3b, v39
	v_cvt_pk_bf16_f32 v5, v215, s0
	v_mov_b32_e32 v2, v249
	ds_write_b16 v2, v5
	v_cvt_pk_bf16_f32 v5, v39, s0
	v_add_u32_e32 v2, 0x800, v249
	ds_write_b16 v2, v5
	v_cvt_pk_bf16_f32 v5, v219, s0
	v_add_u32_e32 v2, 0x1000, v249
	v_mul_f32_e32 v4, v47, v69
	ds_write_b16 v2, v5
	v_cvt_pk_bf16_f32 v5, v76, s0
	v_add_u32_e32 v2, 0x1800, v249
	v_mul_f32_e32 v56, 0x3fb8aa3b, v56
	ds_write_b16 v2, v5
	v_cvt_pk_bf16_f32 v5, v4, s0
	v_add_u32_e32 v2, 0x2000, v249
	v_exp_f32_e32 v56, v56
	ds_write_b16 v2, v5
	v_mul_f32_e32 v2, v35, v4
	v_cvt_pk_bf16_f32 v4, v2, s0
	v_add_u32_e32 v2, 0x2800, v249
	ds_write_b16 v2, v4
	v_cvt_pk_bf16_f32 v2, v19, s0
	v_add_u32_e32 v0, 0x3000, v249
	v_lshlrev_b32_e32 v70, 16, v70
; DEVINL bf16_t f2bf(float f) { return (bf16_t)(cvt_pk_bf16(f, 0.f) & 0xffffu); }
; DEVINL void rw_project_head(const Ctx& c, int layer, int b, int hd, int pj, int nP, unsigned* cnt, unsigned char* lds) {
;     ...
;             for (int nt = 0; nt < 4; ++nt)
; #pragma unroll
;                 for (int rg = 0; rg < 4; ++rg) {
;                     const size_t o = (size_t)(t0 + kg * 4 + rg) * 512 + hd * 64 + nt * 16 + cl;
;                     const float kk = kkraw[nt][rg] * inv[rg];
;                     R[o] = f2bf(rcv[nt][rg]); LD[o] = f2bf(ldv[nt][rg]); KP[o] = f2bf(kmod[nt][rg]); VP[o] = f2bf(vout[nt][rg]);
;                     KK[o] = f2bf(kk); BB[o] = f2bf(kk * av[nt][rg]); GG[o] = f2bf(gv[nt][rg]);
;                 }
;         }
;         asm volatile("s_waitcnt vmcnt(0)" ::: "memory");
;         __syncthreads();
;         if (threadIdx.x == 0) {
;             __builtin_amdgcn_fence(__ATOMIC_RELEASE, "agent");
;             __hip_atomic_store(cnt, (unsigned)(layer * 16 + round + 1), __ATOMIC_RELAXED, __HIP_MEMORY_SCOPE_AGENT);
;         }
	ds_write_b16 v0, v2
	v_lshlrev_b64 v[0:1], 1, v[120:121]
	v_lshrrev_b32_e32 v249, 3, v0
	v_and_b32_e32 v249, 0x780, v249
	v_and_b32_e32 v250, 0x7e, v0
	v_add3_u32 v249, v249, v250, v251
	v_mul_f32_e32 v56, 0xbfb8aa3b, v56
	v_cvt_pk_bf16_f32 v5, v70, s0
	v_mov_b32_e32 v2, v249
	ds_write_b16 v2, v5
	v_cvt_pk_bf16_f32 v5, v56, s0
	v_add_u32_e32 v2, 0x800, v249
	ds_write_b16 v2, v5
	v_cvt_pk_bf16_f32 v5, v73, s0
	v_add_u32_e32 v2, 0x1000, v249
	v_mul_f32_e32 v4, v150, v228
	ds_write_b16 v2, v5
	v_cvt_pk_bf16_f32 v5, v50, s0
	v_add_u32_e32 v2, 0x1800, v249
	v_mul_f32_e32 v57, 0x3fb8aa3b, v57
	ds_write_b16 v2, v5
	v_cvt_pk_bf16_f32 v5, v4, s0
	v_add_u32_e32 v2, 0x2000, v249
	v_exp_f32_e32 v57, v57
	ds_write_b16 v2, v5
	v_mul_f32_e32 v2, v40, v4
	v_cvt_pk_bf16_f32 v4, v2, s0
	v_add_u32_e32 v2, 0x2800, v249
	ds_write_b16 v2, v4
	v_cvt_pk_bf16_f32 v2, v20, s0
	v_add_u32_e32 v0, 0x3000, v249
	v_lshlrev_b32_e32 v62, 16, v62
	ds_write_b16 v0, v2
	v_lshlrev_b64 v[0:1], 1, v[122:123]
	v_lshrrev_b32_e32 v249, 3, v0
	v_and_b32_e32 v249, 0x780, v249
	v_and_b32_e32 v250, 0x7e, v0
	v_add3_u32 v249, v249, v250, v251
	v_mul_f32_e32 v57, 0xbfb8aa3b, v57
	v_cvt_pk_bf16_f32 v5, v62, s0
	v_mov_b32_e32 v2, v249
	ds_write_b16 v2, v5
	v_cvt_pk_bf16_f32 v5, v57, s0
	v_add_u32_e32 v2, 0x800, v249
	ds_write_b16 v2, v5
	v_cvt_pk_bf16_f32 v5, v67, s0
	v_add_u32_e32 v2, 0x1000, v249
	v_mul_f32_e32 v4, v68, v220
	ds_write_b16 v2, v5
	v_cvt_pk_bf16_f32 v5, v51, s0
	v_add_u32_e32 v2, 0x1800, v249
	v_mul_f32_e32 v55, 0x3fb8aa3b, v55
	ds_write_b16 v2, v5
	v_cvt_pk_bf16_f32 v5, v4, s0
	v_add_u32_e32 v2, 0x2000, v249
	v_exp_f32_e32 v55, v55
	ds_write_b16 v2, v5
	v_mul_f32_e32 v2, v41, v4
	v_cvt_pk_bf16_f32 v4, v2, s0
	v_add_u32_e32 v2, 0x2800, v249
	ds_write_b16 v2, v4
	v_cvt_pk_bf16_f32 v2, v21, s0
	v_add_u32_e32 v0, 0x3000, v249
	v_lshlrev_b32_e32 v53, 16, v53
	ds_write_b16 v0, v2
	v_lshlrev_b64 v[0:1], 1, v[124:125]
	v_lshrrev_b32_e32 v249, 3, v0
	v_and_b32_e32 v249, 0x780, v249
	v_and_b32_e32 v250, 0x7e, v0
	v_add3_u32 v249, v249, v250, v251
	v_mul_f32_e32 v55, 0xbfb8aa3b, v55
	v_cvt_pk_bf16_f32 v5, v53, s0
	v_mov_b32_e32 v2, v249
	ds_write_b16 v2, v5
	v_cvt_pk_bf16_f32 v5, v55, s0
	v_add_u32_e32 v2, 0x800, v249
	ds_write_b16 v2, v5
	v_cvt_pk_bf16_f32 v5, v58, s0
	v_add_u32_e32 v2, 0x1000, v249
	v_mul_f32_e32 v4, v60, v77
	ds_write_b16 v2, v5
	v_cvt_pk_bf16_f32 v5, v48, s0
	v_add_u32_e32 v2, 0x1800, v249
	v_mul_f32_e32 v45, 0x3fb8aa3b, v45
	ds_write_b16 v2, v5
	v_cvt_pk_bf16_f32 v5, v4, s0
	v_add_u32_e32 v2, 0x2000, v249
	v_exp_f32_e32 v45, v45
	ds_write_b16 v2, v5
	v_mul_f32_e32 v2, v42, v4
	v_cvt_pk_bf16_f32 v4, v2, s0
	v_add_u32_e32 v2, 0x2800, v249
	ds_write_b16 v2, v4
	v_cvt_pk_bf16_f32 v2, v22, s0
	v_add_u32_e32 v0, 0x3000, v249
	ds_write_b16 v0, v2
	v_lshlrev_b64 v[0:1], 1, v[126:127]
	v_lshrrev_b32_e32 v249, 3, v0
	v_and_b32_e32 v249, 0x780, v249
	v_and_b32_e32 v250, 0x7e, v0
	v_add3_u32 v249, v249, v250, v251
	v_mul_f32_e32 v45, 0xbfb8aa3b, v45
	v_cvt_pk_bf16_f32 v5, v44, s0
	v_mov_b32_e32 v2, v249
	ds_write_b16 v2, v5
	v_cvt_pk_bf16_f32 v5, v45, s0
	v_add_u32_e32 v2, 0x800, v249
	ds_write_b16 v2, v5
	v_cvt_pk_bf16_f32 v5, v49, s0
	v_add_u32_e32 v2, 0x1000, v249
	v_mul_f32_e32 v4, v52, v69
	ds_write_b16 v2, v5
	v_add_u32_e32 v2, 0x1800, v249
	ds_write_b16 v2, v46
	v_cvt_pk_bf16_f32 v5, v4, s0
	v_add_u32_e32 v2, 0x2000, v249
	ds_write_b16 v2, v5
	v_mul_f32_e32 v2, v43, v4
	v_cvt_pk_bf16_f32 v4, v2, s0
	v_add_u32_e32 v2, 0x2800, v249
	ds_write_b16 v2, v4
	v_cvt_pk_bf16_f32 v2, v23, s0
	v_add_u32_e32 v0, 0x3000, v249
	ds_write_b16 v0, v2
	v_and_b32_e32 v252, 63, v160
	v_lshl_add_u32 v252, v252, 4, v251
	v_and_b32_e32 v253, 0xfffffff0, v195
	v_add_u32_e32 v253, v253, v186
	v_bfe_u32 v254, v160, 3, 3
	v_add_u32_e32 v253, v253, v254
	v_lshlrev_b32_e32 v253, 9, v253
	v_and_b32_e32 v254, 0x1c0, v86
	v_add_u32_e32 v253, v253, v254
	v_and_b32_e32 v254, 7, v160
	v_lshl_add_u32 v253, v254, 3, v253
	v_lshlrev_b32_e32 v254, 1, v253
	v_mov_b32_e32 v255, 0
	v_add_u32_e32 v248, 0x2000, v254
	v_mov_b32_e32 v249, 0
	ds_read_b128 v[8:11], v252 offset:0
	ds_read_b128 v[28:31], v252 offset:1024
	ds_read_b128 v[36:39], v252 offset:2048
	ds_read_b128 v[0:3], v252 offset:3072
	s_waitcnt lgkmcnt(0)
	v_lshl_add_u64 v[4:5], s[22:23], 0, v[254:255]
	global_store_dwordx4 v[4:5], v[8:11], off sc1
	v_lshl_add_u64 v[250:251], s[22:23], 0, v[248:249]
	global_store_dwordx4 v[250:251], v[28:31], off sc1
	v_lshl_add_u64 v[4:5], s[14:15], 0, v[254:255]
	global_store_dwordx4 v[4:5], v[36:39], off sc1
	v_lshl_add_u64 v[250:251], s[14:15], 0, v[248:249]
	global_store_dwordx4 v[250:251], v[0:3], off sc1
	ds_read_b128 v[8:11], v252 offset:4096
	ds_read_b128 v[28:31], v252 offset:5120
	ds_read_b128 v[36:39], v252 offset:6144
	ds_read_b128 v[0:3], v252 offset:7168
	s_waitcnt lgkmcnt(0)
	v_lshl_add_u64 v[4:5], s[0:1], 0, v[254:255]
	global_store_dwordx4 v[4:5], v[8:11], off sc1
	v_lshl_add_u64 v[250:251], s[0:1], 0, v[248:249]
	global_store_dwordx4 v[250:251], v[28:31], off sc1
	v_lshl_add_u64 v[4:5], s[24:25], 0, v[254:255]
	global_store_dwordx4 v[4:5], v[36:39], off sc1
	v_lshl_add_u64 v[250:251], s[24:25], 0, v[248:249]
	global_store_dwordx4 v[250:251], v[0:3], off sc1
	ds_read_b128 v[8:11], v252 offset:8192
	ds_read_b128 v[28:31], v252 offset:9216
	ds_read_b128 v[36:39], v252 offset:10240
	ds_read_b128 v[0:3], v252 offset:11264
	s_waitcnt lgkmcnt(0)
	v_lshl_add_u64 v[4:5], s[28:29], 0, v[254:255]
	global_store_dwordx4 v[4:5], v[8:11], off sc1
	v_lshl_add_u64 v[250:251], s[28:29], 0, v[248:249]
	global_store_dwordx4 v[250:251], v[28:31], off sc1
	v_lshl_add_u64 v[4:5], s[30:31], 0, v[254:255]
	global_store_dwordx4 v[4:5], v[36:39], off sc1
	v_lshl_add_u64 v[250:251], s[30:31], 0, v[248:249]
	global_store_dwordx4 v[250:251], v[0:3], off sc1
	ds_read_b128 v[8:11], v252 offset:12288
	ds_read_b128 v[28:31], v252 offset:13312
	s_waitcnt lgkmcnt(0)
	v_lshl_add_u64 v[4:5], s[34:35], 0, v[254:255]
	global_store_dwordx4 v[4:5], v[8:11], off sc1
	v_lshl_add_u64 v[250:251], s[34:35], 0, v[248:249]
	global_store_dwordx4 v[250:251], v[28:31], off sc1
.LBB0_237:
	s_or_b64 exec, exec, s[12:13]
	s_waitcnt vmcnt(0)
	s_waitcnt vmcnt(63) expcnt(7) lgkmcnt(15)
	s_barrier
	s_mov_b64 s[0:1], exec
	v_cmp_eq_u32_e32 vcc, 0x1c0, v160
	s_nop 0
	s_and_b64 s[12:13], s[0:1], vcc
	s_mov_b64 exec, s[12:13]
	s_cbranch_execz .LBB0_140
	s_add_i32 s12, s16, s20
	s_cmp_lt_u32 s12, s17
	s_cbranch_scc0 .Lpub_do
	s_sub_i32 s13, s19, 1
	s_and_b32 s13, s13, 15
	s_movk_i32 s12, 0x3ff
	s_movk_i32 s14, 0x7f
	s_cmp_eq_u32 s30, 3
	s_cselect_b32 s12, s14, s12
	s_bitcmp1_b32 s12, s13
	s_cbranch_scc0 .LBB0_140
.Lpub_do:
	v_mov_b32_e32 v0, s19
	s_nop 0
	s_waitcnt vmcnt(0)
	global_store_dword v65, v0, s[8:9] sc1
	s_branch .LBB0_140
